# in-proj phase: all stores write-through (incl. gate-column fallback), barrier after it skips the L2 write-back as well
# baseline (speedup 1.0000x reference)
.LBB0_53:
	s_andn2_saveexec_b64 s[8:9], s[22:23]
	s_cbranch_execz .LBB0_73
	s_mov_b64 s[22:23], exec
	v_readlane_b32 s5, v255, 44
	s_cmp_lt_i32 s5, 0
	s_cbranch_scc1 .Lbar_do_wb
	s_cmp_lg_u32 s5, 1
	s_cbranch_scc1 .Lbar_skip_wb
.Lbar_do_wb:
	buffer_wbl2 sc1

.LBB0_378:
	s_mul_i32 s52, s19, 0x104
	s_mul_i32 s20, s14, 0x104
	v_add_u32_e32 v12, s52, v178
	v_add_u32_e32 v13, s20, v178
	ds_read2_b32 v[4:5], v12 offset1:130
	ds_read2_b32 v[6:7], v13 offset1:130
	s_mul_i32 s20, s19, s6
	s_mul_i32 s52, s14, s13
	v_lshl_add_u64 v[8:9], s[20:21], 2, v[2:3]
	s_mov_b32 s53, s21
	s_add_i32 s20, s19, 2
	v_lshl_add_u64 v[10:11], s[52:53], 2, v[2:3]
	s_add_i32 s52, s14, 2
	s_mul_i32 s20, s20, s6
	s_waitcnt lgkmcnt(0)
	global_store_dword v[8:9], v4, off sc1
	global_store_dword v[10:11], v6, off sc1
	s_mul_i32 s52, s52, s13
	v_lshl_add_u64 v[8:9], s[20:21], 2, v[2:3]
	v_lshl_add_u64 v[10:11], s[52:53], 2, v[2:3]
	global_store_dword v[8:9], v5, off sc1
	global_store_dword v[10:11], v7, off sc1
	v_add_u32_e32 v4, 0x400, v12
	ds_read2_b32 v[4:5], v4 offset0:4 offset1:134
	v_add_u32_e32 v6, 0x400, v13
	s_add_i32 s20, s19, 4
	ds_read2_b32 v[6:7], v6 offset0:4 offset1:134
	s_add_i32 s52, s14, 4
	s_mul_i32 s20, s20, s6
	s_mul_i32 s52, s52, s13
	v_lshl_add_u64 v[8:9], s[20:21], 2, v[2:3]
	s_add_i32 s20, s19, 6
	v_lshl_add_u64 v[10:11], s[52:53], 2, v[2:3]
	s_add_i32 s52, s14, 6
	s_mul_i32 s20, s20, s6
	s_add_i32 s19, s19, 8
	s_add_i32 s14, s14, 8
	s_add_i32 s37, s37, -8
	s_waitcnt lgkmcnt(0)
	global_store_dword v[8:9], v4, off sc1
	global_store_dword v[10:11], v6, off sc1
	s_mul_i32 s52, s52, s13
	v_lshl_add_u64 v[8:9], s[20:21], 2, v[2:3]
	s_cmp_lg_u32 s37, 0
	v_lshl_add_u64 v[10:11], s[52:53], 2, v[2:3]
	global_store_dword v[8:9], v5, off sc1
	global_store_dword v[10:11], v7, off sc1
	s_cbranch_scc1 .LBB0_378

.LBB0_382:
	s_mul_i32 s20, s13, 0x104
	s_mul_i32 s19, s6, 0x104
	v_add_u32_e32 v12, s20, v178
	v_add_u32_e32 v13, s19, v178
	ds_read2_b32 v[4:5], v12 offset1:130
	ds_read2_b32 v[6:7], v13 offset1:130
	s_mul_i32 s20, s13, 0xd10
	s_mul_i32 s22, s6, 0xd10
	s_mov_b32 s23, s21
	s_waitcnt lgkmcnt(0)
	v_and_b32_sdwa v9, v4, v193 dst_sel:DWORD dst_unused:UNUSED_PAD src0_sel:WORD_1 src1_sel:DWORD
	v_and_b32_sdwa v8, v6, v193 dst_sel:DWORD dst_unused:UNUSED_PAD src0_sel:WORD_1 src1_sel:DWORD
	v_add3_u32 v6, v6, v8, s87
	v_add3_u32 v4, v4, v9, s87
	v_lshl_add_u64 v[8:9], s[20:21], 1, v[2:3]
	v_lshl_add_u64 v[10:11], s[22:23], 1, v[2:3]
	global_store_short_d16_hi v[8:9], v4, off sc1
	global_store_short_d16_hi v[10:11], v6, off sc1
	v_and_b32_sdwa v4, v7, v193 dst_sel:DWORD dst_unused:UNUSED_PAD src0_sel:WORD_1 src1_sel:DWORD
	v_and_b32_sdwa v6, v5, v193 dst_sel:DWORD dst_unused:UNUSED_PAD src0_sel:WORD_1 src1_sel:DWORD
	s_add_i32 s26, s22, 0x1a20
	s_add_i32 s36, s20, 0x1a20
	s_mov_b32 s37, s21
	s_mov_b32 s27, s21
	v_add3_u32 v8, v7, v4, s87
	v_add3_u32 v9, v5, v6, s87
	v_lshl_add_u64 v[4:5], s[36:37], 1, v[2:3]
	v_lshl_add_u64 v[6:7], s[26:27], 1, v[2:3]
	global_store_short_d16_hi v[4:5], v9, off sc1
	global_store_short_d16_hi v[6:7], v8, off sc1
	v_add_u32_e32 v4, 0x400, v12
	v_add_u32_e32 v6, 0x400, v13
	ds_read2_b32 v[4:5], v4 offset0:4 offset1:134
	ds_read2_b32 v[6:7], v6 offset0:4 offset1:134
	s_add_i32 s36, s20, 0x3440
	s_add_i32 s26, s22, 0x3440
	v_lshl_add_u64 v[10:11], s[26:27], 1, v[2:3]
	s_waitcnt lgkmcnt(0)
	v_and_b32_sdwa v9, v4, v193 dst_sel:DWORD dst_unused:UNUSED_PAD src0_sel:WORD_1 src1_sel:DWORD
	v_and_b32_sdwa v8, v6, v193 dst_sel:DWORD dst_unused:UNUSED_PAD src0_sel:WORD_1 src1_sel:DWORD
	v_add3_u32 v6, v6, v8, s87
	v_add3_u32 v4, v4, v9, s87
	v_lshl_add_u64 v[8:9], s[36:37], 1, v[2:3]
	global_store_short_d16_hi v[8:9], v4, off sc1
	global_store_short_d16_hi v[10:11], v6, off sc1
	v_and_b32_sdwa v4, v7, v193 dst_sel:DWORD dst_unused:UNUSED_PAD src0_sel:WORD_1 src1_sel:DWORD
	v_and_b32_sdwa v6, v5, v193 dst_sel:DWORD dst_unused:UNUSED_PAD src0_sel:WORD_1 src1_sel:DWORD
	s_addk_i32 s22, 0x4e60
	s_addk_i32 s20, 0x4e60
	s_add_i32 s13, s13, 8
	s_add_i32 s6, s6, 8
	s_add_i32 s14, s14, -8
	v_add3_u32 v8, v7, v4, s87
	v_add3_u32 v9, v5, v6, s87
	v_lshl_add_u64 v[4:5], s[20:21], 1, v[2:3]
	s_cmp_eq_u32 s14, 0
	v_lshl_add_u64 v[6:7], s[22:23], 1, v[2:3]
	global_store_short_d16_hi v[4:5], v9, off sc1
	global_store_short_d16_hi v[6:7], v8, off sc1
	s_cbranch_scc0 .LBB0_382
	s_mov_b64 s[22:23], 0

.LBB0_386:
	s_mul_i32 s13, s53, 0x104
	s_mul_i32 s6, s56, 0x104
	s_add_i32 s6, s72, s6
	s_add_i32 s13, s72, s13
	v_lshlrev_b32_e32 v4, 2, v98
	v_add_u32_e32 v5, s6, v4
	v_add_u32_e32 v7, s13, v4
	s_add_i32 s14, s56, s49
	ds_read_b32 v6, v5
	ds_read_b32 v7, v7
	v_add_u32_e32 v5, s6, v220
	v_add_u32_e32 v9, s13, v220
	s_add_i32 s19, s53, s52
	s_ashr_i32 s14, s14, 6
	ds_read_b32 v8, v5
	ds_read_b32 v9, v9
	s_ashr_i32 s19, s19, 6
	v_mov_b32_e32 v5, s56
	v_mov_b32_e32 v10, s14
	v_cndmask_b32_e64 v5, v5, v10, s[38:39]
	v_mov_b32_e32 v10, s53
	v_mov_b32_e32 v11, s19
	v_cndmask_b32_e64 v10, v10, v11, s[38:39]
	v_lshlrev_b32_e32 v5, 4, v5
	v_lshlrev_b32_e32 v10, 4, v10
	v_or_b32_e32 v12, v5, v100
	v_or_b32_e32 v10, v10, v99
	v_ashrrev_i32_e32 v13, 31, v12
	v_ashrrev_i32_e32 v11, 31, v10
	v_lshlrev_b64 v[12:13], 2, v[12:13]
	v_lshl_add_u64 v[14:15], s[42:43], 0, v[12:13]
	v_lshlrev_b64 v[10:11], 2, v[10:11]
	v_lshl_add_u64 v[12:13], s[44:45], 0, v[12:13]
	v_lshl_add_u64 v[16:17], s[42:43], 0, v[10:11]
	global_load_dword v14, v[14:15], off
	s_nop 0
	global_load_dword v15, v[16:17], off
	v_lshl_add_u64 v[10:11], s[44:45], 0, v[10:11]
	global_load_dword v12, v[12:13], off
	s_nop 0
	global_load_dword v13, v[10:11], off
	s_mul_i32 s22, s53, 0xd10
	s_mul_i32 s20, s56, 0xd10
	s_mov_b32 s23, s21
	s_add_i32 s26, s13, 0x208
	s_add_i32 s19, s56, 2
	s_add_i32 s14, s53, 2
	s_add_i32 s36, s20, 0x1a20
	s_mov_b32 s37, s21
	s_mov_b32 s27, s21
	s_add_i32 s57, s57, -8
	s_waitcnt vmcnt(0) lgkmcnt(0)
	v_pk_mul_f32 v[8:9], v[8:9], v[12:13]
	s_nop 0
	v_pk_add_f32 v[10:11], v[8:9], 0 neg_lo:[1,1] neg_hi:[1,1]
	s_nop 0
	v_cndmask_b32_e64 v9, v9, v11, s[40:41]
	v_cndmask_b32_e64 v8, v8, v10, s[40:41]
	v_pk_fma_f32 v[6:7], v[6:7], v[14:15], v[8:9]
	s_nop 0
	v_and_b32_sdwa v5, v7, v193 dst_sel:DWORD dst_unused:UNUSED_PAD src0_sel:WORD_1 src1_sel:DWORD
	v_and_b32_sdwa v8, v6, v193 dst_sel:DWORD dst_unused:UNUSED_PAD src0_sel:WORD_1 src1_sel:DWORD
	v_add3_u32 v5, v7, v5, s87
	v_add3_u32 v10, v6, v8, s87
	v_lshl_add_u64 v[6:7], s[20:21], 1, v[2:3]
	v_lshl_add_u64 v[8:9], s[22:23], 1, v[2:3]
	s_add_i32 s23, s6, 0x208
	global_store_short_d16_hi v[6:7], v10, off sc1
	global_store_short_d16_hi v[8:9], v5, off sc1
	v_add_u32_e32 v5, s23, v4
	v_add_u32_e32 v7, s26, v4
	ds_read_b32 v6, v5
	ds_read_b32 v7, v7
	v_add_u32_e32 v5, s23, v220
	s_add_i32 s23, s19, s49
	v_add_u32_e32 v9, s26, v220
	s_add_i32 s26, s14, s52
	s_ashr_i32 s23, s23, 6
	ds_read_b32 v8, v5
	ds_read_b32 v9, v9
	s_ashr_i32 s26, s26, 6
	v_mov_b32_e32 v5, s19
	v_mov_b32_e32 v10, s23
	v_cndmask_b32_e64 v5, v5, v10, s[38:39]
	v_mov_b32_e32 v10, s14
	v_mov_b32_e32 v11, s26
	v_cndmask_b32_e64 v10, v10, v11, s[38:39]
	v_lshlrev_b32_e32 v5, 4, v5
	v_lshlrev_b32_e32 v10, 4, v10
	v_or_b32_e32 v12, v5, v100
	v_or_b32_e32 v10, v10, v99
	v_ashrrev_i32_e32 v13, 31, v12
	v_ashrrev_i32_e32 v11, 31, v10
	v_lshlrev_b64 v[12:13], 2, v[12:13]
	v_lshl_add_u64 v[14:15], s[42:43], 0, v[12:13]
	v_lshlrev_b64 v[10:11], 2, v[10:11]
	v_lshl_add_u64 v[12:13], s[44:45], 0, v[12:13]
	v_lshl_add_u64 v[16:17], s[42:43], 0, v[10:11]
	global_load_dword v14, v[14:15], off
	s_nop 0
	global_load_dword v15, v[16:17], off
	v_lshl_add_u64 v[10:11], s[44:45], 0, v[10:11]
	global_load_dword v12, v[12:13], off
	s_nop 0
	global_load_dword v13, v[10:11], off
	s_add_i32 s26, s22, 0x1a20
	s_add_i32 s23, s6, 0x410
	s_add_i32 s19, s56, 4
	s_add_i32 s14, s53, 4
	s_addk_i32 s6, 0x618
	s_waitcnt vmcnt(0) lgkmcnt(0)
	v_pk_mul_f32 v[8:9], v[8:9], v[12:13]
	s_nop 0
	v_pk_add_f32 v[10:11], v[8:9], 0 neg_lo:[1,1] neg_hi:[1,1]
	s_nop 0
	v_cndmask_b32_e64 v9, v9, v11, s[40:41]
	v_cndmask_b32_e64 v8, v8, v10, s[40:41]
	v_pk_fma_f32 v[6:7], v[6:7], v[14:15], v[8:9]
	s_nop 0
	v_and_b32_sdwa v5, v7, v193 dst_sel:DWORD dst_unused:UNUSED_PAD src0_sel:WORD_1 src1_sel:DWORD
	v_and_b32_sdwa v8, v6, v193 dst_sel:DWORD dst_unused:UNUSED_PAD src0_sel:WORD_1 src1_sel:DWORD
	v_add3_u32 v5, v7, v5, s87
	v_add3_u32 v10, v6, v8, s87
	v_lshl_add_u64 v[6:7], s[36:37], 1, v[2:3]
	v_lshl_add_u64 v[8:9], s[26:27], 1, v[2:3]
	s_add_i32 s26, s13, 0x410
	global_store_short_d16_hi v[6:7], v10, off sc1
	global_store_short_d16_hi v[8:9], v5, off sc1
	v_add_u32_e32 v5, s23, v4
	v_add_u32_e32 v7, s26, v4
	ds_read_b32 v6, v5
	ds_read_b32 v7, v7
	v_add_u32_e32 v5, s23, v220
	s_add_i32 s23, s19, s49
	v_add_u32_e32 v9, s26, v220
	s_add_i32 s26, s14, s52
	s_ashr_i32 s23, s23, 6
	ds_read_b32 v8, v5
	ds_read_b32 v9, v9
	s_ashr_i32 s26, s26, 6
	v_mov_b32_e32 v5, s19
	v_mov_b32_e32 v10, s23
	v_cndmask_b32_e64 v5, v5, v10, s[38:39]
	v_mov_b32_e32 v10, s14
	v_mov_b32_e32 v11, s26
	v_cndmask_b32_e64 v10, v10, v11, s[38:39]
	v_lshlrev_b32_e32 v5, 4, v5
	v_lshlrev_b32_e32 v10, 4, v10
	v_or_b32_e32 v12, v5, v100
	v_or_b32_e32 v10, v10, v99
	v_ashrrev_i32_e32 v13, 31, v12
	v_ashrrev_i32_e32 v11, 31, v10
	v_lshlrev_b64 v[12:13], 2, v[12:13]
	v_lshl_add_u64 v[14:15], s[42:43], 0, v[12:13]
	v_lshlrev_b64 v[10:11], 2, v[10:11]
	v_lshl_add_u64 v[12:13], s[44:45], 0, v[12:13]
	v_lshl_add_u64 v[16:17], s[42:43], 0, v[10:11]
	global_load_dword v14, v[14:15], off
	s_nop 0
	global_load_dword v15, v[16:17], off
	v_lshl_add_u64 v[10:11], s[44:45], 0, v[10:11]
	global_load_dword v12, v[12:13], off
	s_nop 0
	global_load_dword v13, v[10:11], off
	s_add_i32 s36, s20, 0x3440
	s_add_i32 s26, s22, 0x3440
	s_addk_i32 s13, 0x618
	s_add_i32 s19, s56, 6
	s_add_i32 s14, s53, 6
	s_addk_i32 s22, 0x4e60
	s_addk_i32 s20, 0x4e60
	s_add_i32 s56, s56, 8
	s_add_i32 s53, s53, 8
	s_mov_b32 s23, s21
	s_waitcnt vmcnt(0) lgkmcnt(0)
	v_pk_mul_f32 v[8:9], v[8:9], v[12:13]
	s_nop 0
	v_pk_add_f32 v[10:11], v[8:9], 0 neg_lo:[1,1] neg_hi:[1,1]
	s_nop 0
	v_cndmask_b32_e64 v9, v9, v11, s[40:41]
	v_cndmask_b32_e64 v8, v8, v10, s[40:41]
	v_pk_fma_f32 v[6:7], v[6:7], v[14:15], v[8:9]
	s_nop 0
	v_and_b32_sdwa v5, v7, v193 dst_sel:DWORD dst_unused:UNUSED_PAD src0_sel:WORD_1 src1_sel:DWORD
	v_and_b32_sdwa v8, v6, v193 dst_sel:DWORD dst_unused:UNUSED_PAD src0_sel:WORD_1 src1_sel:DWORD
	v_add3_u32 v5, v7, v5, s87
	v_add3_u32 v10, v6, v8, s87
	v_lshl_add_u64 v[6:7], s[36:37], 1, v[2:3]
	v_lshl_add_u64 v[8:9], s[26:27], 1, v[2:3]
	global_store_short_d16_hi v[6:7], v10, off sc1
	global_store_short_d16_hi v[8:9], v5, off sc1
	v_add_u32_e32 v5, s6, v4
	v_add_u32_e32 v6, s13, v4
	ds_read_b32 v4, v5
	ds_read_b32 v5, v6
	v_add_u32_e32 v6, s6, v220
	s_add_i32 s6, s19, s49
	v_add_u32_e32 v7, s13, v220
	s_add_i32 s13, s14, s52
	s_ashr_i32 s6, s6, 6
	s_ashr_i32 s13, s13, 6
	v_mov_b32_e32 v8, s19
	v_mov_b32_e32 v9, s6
	v_cndmask_b32_e64 v8, v8, v9, s[38:39]
	v_mov_b32_e32 v9, s14
	v_mov_b32_e32 v10, s13
	v_cndmask_b32_e64 v9, v9, v10, s[38:39]
	v_lshlrev_b32_e32 v10, 4, v8
	v_lshlrev_b32_e32 v9, 4, v9
	v_or_b32_e32 v10, v10, v100
	v_or_b32_e32 v8, v9, v99
	v_ashrrev_i32_e32 v11, 31, v10
	v_ashrrev_i32_e32 v9, 31, v8
	v_lshlrev_b64 v[10:11], 2, v[10:11]
	v_lshl_add_u64 v[12:13], s[42:43], 0, v[10:11]
	v_lshlrev_b64 v[8:9], 2, v[8:9]
	v_lshl_add_u64 v[10:11], s[44:45], 0, v[10:11]
	ds_read_b32 v6, v6
	ds_read_b32 v7, v7
	v_lshl_add_u64 v[14:15], s[42:43], 0, v[8:9]
	global_load_dword v12, v[12:13], off
	s_nop 0
	global_load_dword v13, v[14:15], off
	v_lshl_add_u64 v[8:9], s[44:45], 0, v[8:9]
	global_load_dword v10, v[10:11], off
	s_nop 0
	global_load_dword v11, v[8:9], off
	s_cmp_eq_u32 s57, 0
	s_waitcnt vmcnt(0) lgkmcnt(0)
	v_pk_mul_f32 v[6:7], v[6:7], v[10:11]
	s_nop 0
	v_pk_add_f32 v[8:9], v[6:7], 0 neg_lo:[1,1] neg_hi:[1,1]
	s_nop 0
	v_cndmask_b32_e64 v7, v7, v9, s[40:41]
	v_cndmask_b32_e64 v6, v6, v8, s[40:41]
	v_pk_fma_f32 v[4:5], v[4:5], v[12:13], v[6:7]
	s_nop 0
	v_and_b32_sdwa v6, v5, v193 dst_sel:DWORD dst_unused:UNUSED_PAD src0_sel:WORD_1 src1_sel:DWORD
	v_and_b32_sdwa v7, v4, v193 dst_sel:DWORD dst_unused:UNUSED_PAD src0_sel:WORD_1 src1_sel:DWORD
	v_add3_u32 v8, v5, v6, s87
	v_add3_u32 v9, v4, v7, s87
	v_lshl_add_u64 v[4:5], s[20:21], 1, v[2:3]
	v_lshl_add_u64 v[6:7], s[22:23], 1, v[2:3]
	global_store_short_d16_hi v[4:5], v9, off sc1
	global_store_short_d16_hi v[6:7], v8, off sc1
	s_cbranch_scc0 .LBB0_386

.LBB0_389:
	v_add_u32_e32 v8, s13, v179
	ds_read2_b32 v[4:5], v8 offset1:1
	s_lshl_b32 s20, s14, 5
	s_lshl_b32 s22, s6, 5
	s_mov_b32 s23, s21
	s_add_i32 s34, s20, 64
	s_waitcnt lgkmcnt(0)
	v_and_b32_sdwa v6, v5, v193 dst_sel:DWORD dst_unused:UNUSED_PAD src0_sel:WORD_1 src1_sel:DWORD
	v_and_b32_sdwa v7, v4, v193 dst_sel:DWORD dst_unused:UNUSED_PAD src0_sel:WORD_1 src1_sel:DWORD
	v_add3_u32 v9, v5, v6, s87
	v_add3_u32 v10, v4, v7, s87
	v_lshl_add_u64 v[4:5], s[20:21], 1, v[2:3]
	v_lshl_add_u64 v[6:7], s[22:23], 1, v[2:3]
	global_store_short_d16_hi v[4:5], v10, off sc1
	global_store_short_d16_hi v[6:7], v9, off sc1
	ds_read2_b32 v[4:5], v8 offset0:2 offset1:3
	s_mov_b32 s35, s21
	s_add_i32 s26, s22, 64
	s_mov_b32 s27, s21
	s_add_i32 s14, s14, 8
	s_waitcnt lgkmcnt(0)
	v_and_b32_sdwa v6, v5, v193 dst_sel:DWORD dst_unused:UNUSED_PAD src0_sel:WORD_1 src1_sel:DWORD
	v_and_b32_sdwa v7, v4, v193 dst_sel:DWORD dst_unused:UNUSED_PAD src0_sel:WORD_1 src1_sel:DWORD
	v_add3_u32 v9, v5, v6, s87
	v_add3_u32 v10, v4, v7, s87
	v_lshl_add_u64 v[4:5], s[34:35], 1, v[2:3]
	v_lshl_add_u64 v[6:7], s[26:27], 1, v[2:3]
	global_store_short_d16_hi v[4:5], v10, off sc1
	global_store_short_d16_hi v[6:7], v9, off sc1
	ds_read2_b32 v[4:5], v8 offset0:4 offset1:5
	s_add_i32 s34, s20, 0x80
	s_add_i32 s26, s22, 0x80
	s_addk_i32 s22, 0xc0
	s_addk_i32 s20, 0xc0
	s_waitcnt lgkmcnt(0)
	v_and_b32_sdwa v6, v5, v193 dst_sel:DWORD dst_unused:UNUSED_PAD src0_sel:WORD_1 src1_sel:DWORD
	v_and_b32_sdwa v7, v4, v193 dst_sel:DWORD dst_unused:UNUSED_PAD src0_sel:WORD_1 src1_sel:DWORD
	v_add3_u32 v9, v5, v6, s87
	v_add3_u32 v10, v4, v7, s87
	v_lshl_add_u64 v[4:5], s[34:35], 1, v[2:3]
	v_lshl_add_u64 v[6:7], s[26:27], 1, v[2:3]
	global_store_short_d16_hi v[4:5], v10, off sc1
	global_store_short_d16_hi v[6:7], v9, off sc1
	ds_read2_b32 v[4:5], v8 offset0:6 offset1:7
	s_add_i32 s6, s6, 8
	s_add_i32 s13, s13, 32
	s_cmpk_lg_i32 s13, 0x100
	s_waitcnt lgkmcnt(0)
	v_and_b32_sdwa v6, v5, v193 dst_sel:DWORD dst_unused:UNUSED_PAD src0_sel:WORD_1 src1_sel:DWORD
	v_and_b32_sdwa v7, v4, v193 dst_sel:DWORD dst_unused:UNUSED_PAD src0_sel:WORD_1 src1_sel:DWORD
	v_add3_u32 v8, v5, v6, s87
	v_add3_u32 v9, v4, v7, s87
	v_lshl_add_u64 v[4:5], s[20:21], 1, v[2:3]
	v_lshl_add_u64 v[6:7], s[22:23], 1, v[2:3]
	global_store_short_d16_hi v[4:5], v9, off sc1
	global_store_short_d16_hi v[6:7], v8, off sc1
	s_cbranch_scc1 .LBB0_389

.LBB0_391:
	s_and_b64 vcc, exec, s[26:27]
	s_cbranch_vccz .LBB0_344
	global_load_dword v2, v[112:113], off
	ds_read_b32 v3, v129
	v_or_b32_e32 v4, s76, v101
	v_ashrrev_i32_e32 v5, 31, v4
	v_lshlrev_b64 v[4:5], 6, v[4:5]
	v_lshl_add_u64 v[4:5], v[110:111], 0, v[4:5]
	s_waitcnt vmcnt(0) lgkmcnt(0)
	v_add_f32_e32 v3, v2, v3
	global_store_dword v[4:5], v3, off sc1
	v_add_u32_e32 v3, 0x410, v129
	ds_read_b32 v3, v3
	v_or_b32_e32 v4, 4, v101
	v_or_b32_e32 v4, s76, v4
	v_ashrrev_i32_e32 v5, 31, v4
	v_lshlrev_b64 v[4:5], 6, v[4:5]
	s_waitcnt lgkmcnt(0)
	v_add_f32_e32 v3, v2, v3
	v_lshl_add_u64 v[4:5], v[110:111], 0, v[4:5]
	global_store_dword v[4:5], v3, off sc1
	v_add_u32_e32 v3, 0x820, v129
	ds_read_b32 v3, v3
	v_or_b32_e32 v4, 8, v101
	v_or_b32_e32 v4, s76, v4
	v_ashrrev_i32_e32 v5, 31, v4
	v_lshlrev_b64 v[4:5], 6, v[4:5]
	s_waitcnt lgkmcnt(0)
	v_add_f32_e32 v3, v2, v3
	v_lshl_add_u64 v[4:5], v[110:111], 0, v[4:5]
	global_store_dword v[4:5], v3, off sc1
	v_add_u32_e32 v3, 0xc30, v129
	ds_read_b32 v3, v3
	v_or_b32_e32 v4, 12, v101
	v_or_b32_e32 v4, s76, v4
	v_ashrrev_i32_e32 v5, 31, v4
	v_lshlrev_b64 v[4:5], 6, v[4:5]
	s_waitcnt lgkmcnt(0)
	v_add_f32_e32 v3, v2, v3
	v_lshl_add_u64 v[4:5], v[110:111], 0, v[4:5]
	global_store_dword v[4:5], v3, off sc1
	v_add_u32_e32 v3, 0x1040, v129
	ds_read_b32 v3, v3
	v_or_b32_e32 v4, 16, v101
	v_or_b32_e32 v4, s76, v4
	v_ashrrev_i32_e32 v5, 31, v4
	v_lshlrev_b64 v[4:5], 6, v[4:5]
	s_waitcnt lgkmcnt(0)
	v_add_f32_e32 v3, v2, v3
	v_lshl_add_u64 v[4:5], v[110:111], 0, v[4:5]
	global_store_dword v[4:5], v3, off sc1
	ds_read_b32 v3, v130
	v_or_b32_e32 v4, 20, v101
	v_or_b32_e32 v4, s76, v4
	v_ashrrev_i32_e32 v5, 31, v4
	v_lshlrev_b64 v[4:5], 6, v[4:5]
	s_waitcnt lgkmcnt(0)
	v_add_f32_e32 v3, v2, v3
	v_lshl_add_u64 v[4:5], v[110:111], 0, v[4:5]
	global_store_dword v[4:5], v3, off sc1
	ds_read_b32 v3, v132
	v_or_b32_e32 v4, s76, v131
	v_ashrrev_i32_e32 v5, 31, v4
	v_lshlrev_b64 v[4:5], 6, v[4:5]
	v_lshl_add_u64 v[4:5], v[110:111], 0, v[4:5]
	s_waitcnt lgkmcnt(0)
	v_add_f32_e32 v3, v2, v3
	global_store_dword v[4:5], v3, off sc1
	ds_read_b32 v3, v134
	v_or_b32_e32 v4, s76, v133
	v_ashrrev_i32_e32 v5, 31, v4
	v_lshlrev_b64 v[4:5], 6, v[4:5]
	v_lshl_add_u64 v[4:5], v[110:111], 0, v[4:5]
	s_waitcnt lgkmcnt(0)
	v_add_f32_e32 v3, v2, v3
	global_store_dword v[4:5], v3, off sc1
	ds_read_b32 v3, v161
	v_or_b32_e32 v4, s76, v135
	v_ashrrev_i32_e32 v5, 31, v4
	v_lshlrev_b64 v[4:5], 6, v[4:5]
	v_lshl_add_u64 v[4:5], v[110:111], 0, v[4:5]
	s_waitcnt lgkmcnt(0)
	v_add_f32_e32 v3, v2, v3
	global_store_dword v[4:5], v3, off sc1
	ds_read_b32 v3, v164
	v_or_b32_e32 v4, s76, v163
	v_ashrrev_i32_e32 v5, 31, v4
	v_lshlrev_b64 v[4:5], 6, v[4:5]
	v_lshl_add_u64 v[4:5], v[110:111], 0, v[4:5]
	s_waitcnt lgkmcnt(0)
	v_add_f32_e32 v3, v2, v3
	global_store_dword v[4:5], v3, off sc1
	ds_read_b32 v3, v166
	v_or_b32_e32 v4, s76, v165
	v_ashrrev_i32_e32 v5, 31, v4
	v_lshlrev_b64 v[4:5], 6, v[4:5]
	v_lshl_add_u64 v[4:5], v[110:111], 0, v[4:5]
	s_waitcnt lgkmcnt(0)
	v_add_f32_e32 v3, v2, v3
	global_store_dword v[4:5], v3, off sc1
	ds_read_b32 v3, v168
	v_or_b32_e32 v4, s76, v167
	v_ashrrev_i32_e32 v5, 31, v4
	v_lshlrev_b64 v[4:5], 6, v[4:5]
	v_lshl_add_u64 v[4:5], v[110:111], 0, v[4:5]
	s_waitcnt lgkmcnt(0)
	v_add_f32_e32 v3, v2, v3
	global_store_dword v[4:5], v3, off sc1
	ds_read_b32 v3, v170
	v_or_b32_e32 v4, s76, v169
	v_ashrrev_i32_e32 v5, 31, v4
	v_lshlrev_b64 v[4:5], 6, v[4:5]
	v_lshl_add_u64 v[4:5], v[110:111], 0, v[4:5]
	s_waitcnt lgkmcnt(0)
	v_add_f32_e32 v3, v2, v3
	global_store_dword v[4:5], v3, off sc1
	ds_read_b32 v3, v172
	v_or_b32_e32 v4, s76, v171
	v_ashrrev_i32_e32 v5, 31, v4
	v_lshlrev_b64 v[4:5], 6, v[4:5]
	v_lshl_add_u64 v[4:5], v[110:111], 0, v[4:5]
	s_waitcnt lgkmcnt(0)
	v_add_f32_e32 v3, v2, v3
	global_store_dword v[4:5], v3, off sc1
	ds_read_b32 v3, v174
	v_or_b32_e32 v4, s76, v173
	v_ashrrev_i32_e32 v5, 31, v4
	v_lshlrev_b64 v[4:5], 6, v[4:5]
	v_lshl_add_u64 v[4:5], v[110:111], 0, v[4:5]
	s_waitcnt lgkmcnt(0)
	v_add_f32_e32 v3, v2, v3
	global_store_dword v[4:5], v3, off sc1
	ds_read_b32 v3, v176
	s_waitcnt lgkmcnt(0)
	v_add_f32_e32 v4, v2, v3
	v_or_b32_e32 v2, s76, v175
	v_ashrrev_i32_e32 v3, 31, v2
	v_lshlrev_b64 v[2:3], 6, v[2:3]
	v_lshl_add_u64 v[2:3], v[110:111], 0, v[2:3]
	global_store_dword v[2:3], v4, off sc1
	s_branch .LBB0_344
